# up-GEMM epilogue: 44 ror+select pairs of chain-final row groups merged into one row_shr DPP move writing the carry register
# baseline (speedup 1.0000x reference)
; __device__ __forceinline__ unsigned cvt_pk_bf16(float lo, float hi) { unsigned r; asm volatile("v_cvt_pk_bf16_f32 %0, %1, %2" : "=v"(r) : "v"(lo), "v"(hi)); return r; }
; __device__ __forceinline__ float sigmoid_f(float x) { return __builtin_amdgcn_rcpf(1.0f + __builtin_amdgcn_exp2f(-1.4426950408889634f * x)); }
; __device__ __forceinline__ float dpp_ror1(float v) { return __builtin_bit_cast(float, __builtin_amdgcn_update_dpp(0, __builtin_bit_cast(int, v), 0x121, 0xf, 0xf, false)); }
; __device__ __forceinline__ float dpp_ror2(float v) { return __builtin_bit_cast(float, __builtin_amdgcn_update_dpp(0, __builtin_bit_cast(int, v), 0x122, 0xf, 0xf, false)); }
; __device__ __forceinline__ float fma_s(float a, float b, float c) { float r; asm("v_fma_f32 %0, %1, %2, %3" : "=v"(r) : "v"(a), "v"(b), "v"(c)); return r; }
;     __device__ __forceinline__ void operator()(const f32x4 (&acc)[2][2][4][2], const Unit& u, int wr, int wc, int fr, int fq) const {
;     ...
;                 for (int m = 0; m < 4; ++m) {
;                     f32x4 cur[2] = {acc[ai][0][m][n] * r2v[ai][m], acc[ai][1][m][n] * r2v[ai][m]};
;                     if (first && ai == 0 && wr == 0 && m == 0 && fr < 2) { cur[0] = zero4; cur[1] = zero4; }
;                     f32x4 r1[2], r2[2], av[2];
; #pragma unroll
;                     for (int bj = 0; bj < 2; ++bj)
; #pragma unroll
;                         for (int e = 0; e < 4; ++e) { r1[bj][e] = dpp_ror1(cur[bj][e]); r2[bj][e] = dpp_ror2(cur[bj][e]); }
; #pragma unroll
;                     for (int bj = 0; bj < 2; ++bj)
; #pragma unroll
;                         for (int e = 0; e < 4; ++e) { const float p1 = fr >= 1 ? r1[bj][e] : pr1[bj][e], p2 = fr >= 2 ? r2[bj][e] : pr2[bj][e];
;                             av[bj][e] = fma_s(w0[bj][e], p2, fma_s(w1[bj][e], p1, fma_s(w2[bj][e], cur[bj][e], bb[bj][e]))); }
;                     float o[4];
; #pragma unroll
;                     for (int e = 0; e < 4; ++e) o[e] = av[0][e] * sigmoid_f(av[0][e]) * av[1][e];
;                     const int lr = ai * HALF + wr * 64 + m * 16 + fr, t = t0 + lr;
;                     if (lr >= 2 && t < 4096) { u32x2 w; w.x = cvt_pk_bf16(o[0], o[1]); w.y = cvt_pk_bf16(o[2], o[3]);
;                         *(u32x2*)(gout + (size_t)(b * 4096 + t) * FF + j0 + n * 4) = w; }
.LBB0_902:
	s_or_b64 exec, exec, s[64:65]
	v_pk_mul_f32 v[72:73], v[72:73], v[196:197] op_sel_hi:[1,0]
	v_pk_mul_f32 v[98:99], v[68:69], v[196:197] op_sel_hi:[1,0]
	v_pk_mul_f32 v[96:97], v[70:71], v[196:197] op_sel_hi:[1,0]
	v_mov_b32_dpp v94, v72 row_shr:1 row_mask:0xf bank_mask:0xf
	v_mov_b32_dpp v95, v72 row_shr:2 row_mask:0xf bank_mask:0xf
	v_fma_f32 v72, v148, v72, v152
	v_pk_mul_f32 v[74:75], v[74:75], v[196:197] op_sel_hi:[1,0]
	v_fma_f32 v68, v144, v94, v72
	v_fma_f32 v68, v136, v95, v68
	v_mov_b32_dpp v92, v73 row_shr:1 row_mask:0xf bank_mask:0xf
	v_mov_b32_dpp v93, v73 row_shr:2 row_mask:0xf bank_mask:0xf
	v_fma_f32 v71, v149, v73, v153
	v_fma_f32 v69, v145, v92, v71
	v_fma_f32 v70, v137, v93, v69
	v_mov_b32_dpp v90, v74 row_shr:1 row_mask:0xf bank_mask:0xf
	v_fma_f32 v72, v150, v74, v154
	v_fma_f32 v69, v146, v90, v72
	v_mov_b32_dpp v91, v74 row_shr:2 row_mask:0xf bank_mask:0xf
	v_fma_f32 v72, v138, v91, v69
	v_mov_b32_dpp v87, v75 row_shr:1 row_mask:0xf bank_mask:0xf
	v_fma_f32 v73, v151, v75, v155
	v_fma_f32 v69, v147, v87, v73
	v_mov_b32_dpp v89, v75 row_shr:2 row_mask:0xf bank_mask:0xf
	v_fma_f32 v73, v139, v89, v69
	v_mov_b32_dpp v86, v98 row_shr:1 row_mask:0xf bank_mask:0xf
	v_mov_b32_dpp v88, v98 row_shr:2 row_mask:0xf bank_mask:0xf
	v_fma_f32 v74, v128, v98, v132
	v_fma_f32 v69, v124, v86, v74
	v_fma_f32 v69, v120, v88, v69
	v_mov_b32_dpp v84, v99 row_shr:1 row_mask:0xf bank_mask:0xf
	v_mov_b32_dpp v164, v96 row_ror:1 row_mask:0xf bank_mask:0xf
	v_mov_b32_dpp v85, v99 row_shr:2 row_mask:0xf bank_mask:0xf
	v_fma_f32 v75, v129, v99, v133
	v_fma_f32 v71, v125, v84, v75
	v_fma_f32 v71, v121, v85, v71
	v_cndmask_b32_e64 v74, v164, v82, s[8:9]
	v_mov_b32_dpp v166, v97 row_ror:1 row_mask:0xf bank_mask:0xf
	v_mov_b32_dpp v83, v96 row_shr:2 row_mask:0xf bank_mask:0xf
	v_fma_f32 v82, v130, v96, v134
	s_nop 0
	v_fma_f32 v74, v126, v74, v82
	v_mov_b32_dpp v167, v97 row_ror:2 row_mask:0xf bank_mask:0xf
	v_fma_f32 v74, v122, v83, v74
	v_cndmask_b32_e64 v75, v166, v80, s[8:9]
	v_cndmask_b32_e64 v80, v81, v167, s[10:11]
	v_fma_f32 v81, v131, v97, v135
	s_nop 0
	v_fma_f32 v75, v127, v75, v81
	s_nop 0
	v_fma_f32 v75, v123, v80, v75
	v_add_u32_e32 v80, s71, v214
	v_cmp_gt_i32_e32 vcc, s68, v80
	s_and_b64 s[64:65], s[52:53], vcc
	v_add_u32_e32 v227, s59, v80
	s_and_saveexec_b64 s[76:77], s[64:65]
	s_cbranch_execz .LBB0_904
	v_mul_f32_e32 v80, 0xbfb8aa3b, v73
	v_exp_f32_e32 v80, v80
	s_nop 0
	v_add_f32_e32 v80, 1.0, v80
	v_rcp_f32_e32 v80, v80
	s_nop 0
	v_mul_f32_e32 v73, v73, v80
	v_mul_f32_e32 v73, v73, v75
	v_mul_f32_e32 v75, 0xbfb8aa3b, v72
	v_exp_f32_e32 v75, v75
	s_nop 0
	v_add_f32_e32 v75, 1.0, v75
	v_rcp_f32_e32 v75, v75
	s_nop 0
	v_mul_f32_e32 v72, v72, v75
	v_mul_f32_e32 v72, v72, v74
	v_mul_f32_e32 v74, 0xbfb8aa3b, v70
	v_exp_f32_e32 v74, v74
	s_nop 0
	v_add_f32_e32 v74, 1.0, v74
	v_rcp_f32_e32 v74, v74
	s_nop 0
	v_mul_f32_e32 v70, v70, v74
	v_mul_f32_e32 v70, v70, v71
	v_mul_f32_e32 v71, 0xbfb8aa3b, v68
	v_exp_f32_e32 v71, v71
	s_nop 0
	v_add_f32_e32 v71, 1.0, v71
	v_rcp_f32_e32 v71, v71
	s_nop 0
	v_mul_f32_e32 v68, v68, v71
	v_mul_f32_e32 v68, v68, v69
	v_cvt_pk_bf16_f32 v68, v68, v70
	v_mul_u32_u24_e32 v70, s69, v227
	v_lshl_add_u32 v70, v192, 1, v70
	v_cvt_pk_bf16_f32 v69, v72, v73
	global_store_dwordx2 v70, v[68:69], s[36:37]

; __device__ __forceinline__ unsigned cvt_pk_bf16(float lo, float hi) { unsigned r; asm volatile("v_cvt_pk_bf16_f32 %0, %1, %2" : "=v"(r) : "v"(lo), "v"(hi)); return r; }
; __device__ __forceinline__ float sigmoid_f(float x) { return __builtin_amdgcn_rcpf(1.0f + __builtin_amdgcn_exp2f(-1.4426950408889634f * x)); }
; __device__ __forceinline__ float dpp_ror1(float v) { return __builtin_bit_cast(float, __builtin_amdgcn_update_dpp(0, __builtin_bit_cast(int, v), 0x121, 0xf, 0xf, false)); }
; __device__ __forceinline__ float dpp_ror2(float v) { return __builtin_bit_cast(float, __builtin_amdgcn_update_dpp(0, __builtin_bit_cast(int, v), 0x122, 0xf, 0xf, false)); }
; __device__ __forceinline__ float fma_s(float a, float b, float c) { float r; asm("v_fma_f32 %0, %1, %2, %3" : "=v"(r) : "v"(a), "v"(b), "v"(c)); return r; }
;     __device__ __forceinline__ void operator()(const f32x4 (&acc)[2][2][4][2], const Unit& u, int wr, int wc, int fr, int fq) const {
;     ...
;                 for (int m = 0; m < 4; ++m) {
;                     f32x4 cur[2] = {acc[ai][0][m][n] * r2v[ai][m], acc[ai][1][m][n] * r2v[ai][m]};
;                     if (first && ai == 0 && wr == 0 && m == 0 && fr < 2) { cur[0] = zero4; cur[1] = zero4; }
;                     f32x4 r1[2], r2[2], av[2];
; #pragma unroll
;                     for (int bj = 0; bj < 2; ++bj)
; #pragma unroll
;                         for (int e = 0; e < 4; ++e) { r1[bj][e] = dpp_ror1(cur[bj][e]); r2[bj][e] = dpp_ror2(cur[bj][e]); }
; #pragma unroll
;                     for (int bj = 0; bj < 2; ++bj)
; #pragma unroll
;                         for (int e = 0; e < 4; ++e) { const float p1 = fr >= 1 ? r1[bj][e] : pr1[bj][e], p2 = fr >= 2 ? r2[bj][e] : pr2[bj][e];
;                             av[bj][e] = fma_s(w0[bj][e], p2, fma_s(w1[bj][e], p1, fma_s(w2[bj][e], cur[bj][e], bb[bj][e]))); }
;                     float o[4];
; #pragma unroll
;                     for (int e = 0; e < 4; ++e) o[e] = av[0][e] * sigmoid_f(av[0][e]) * av[1][e];
;                     const int lr = ai * HALF + wr * 64 + m * 16 + fr, t = t0 + lr;
;                     if (lr >= 2 && t < 4096) { u32x2 w; w.x = cvt_pk_bf16(o[0], o[1]); w.y = cvt_pk_bf16(o[2], o[3]);
;                         *(u32x2*)(gout + (size_t)(b * 4096 + t) * FF + j0 + n * 4) = w; }
.LBB0_912:
	s_or_b64 exec, exec, s[86:87]
	v_pk_mul_f32 v[76:77], v[76:77], v[194:195] op_sel_hi:[1,0]
	v_pk_mul_f32 v[118:119], v[64:65], v[194:195] op_sel_hi:[1,0]
	v_pk_mul_f32 v[116:117], v[66:67], v[194:195] op_sel_hi:[1,0]
	v_mov_b32_dpp v170, v76 row_shr:1 row_mask:0xf bank_mask:0xf
	v_mov_b32_dpp v171, v76 row_shr:2 row_mask:0xf bank_mask:0xf
	v_fma_f32 v76, v148, v76, v152
	v_pk_mul_f32 v[78:79], v[78:79], v[194:195] op_sel_hi:[1,0]
	v_fma_f32 v64, v144, v170, v76
	v_mov_b32_dpp v67, v77 row_ror:2 row_mask:0xf bank_mask:0xf
	v_fma_f32 v64, v136, v171, v64
	v_mov_b32_dpp v158, v77 row_shr:1 row_mask:0xf bank_mask:0xf
	v_cndmask_b32_e64 v66, v159, v67, s[10:11]
	v_fma_f32 v67, v149, v77, v153
	v_fma_f32 v65, v145, v158, v67
	v_fma_f32 v66, v137, v66, v65
	v_mov_b32_dpp v156, v78 row_shr:1 row_mask:0xf bank_mask:0xf
	v_mov_b32_dpp v160, v78 row_ror:2 row_mask:0xf bank_mask:0xf
	v_fma_f32 v76, v150, v78, v154
	v_fma_f32 v65, v146, v156, v76
	v_cndmask_b32_e64 v67, v157, v160, s[10:11]
	v_fma_f32 v76, v138, v67, v65
	v_mov_b32_dpp v111, v79 row_shr:1 row_mask:0xf bank_mask:0xf
	v_fma_f32 v77, v151, v79, v155
	v_fma_f32 v65, v147, v111, v77
	v_mov_b32_dpp v143, v79 row_shr:2 row_mask:0xf bank_mask:0xf
	v_fma_f32 v77, v139, v143, v65
	v_mov_b32_dpp v110, v118 row_shr:1 row_mask:0xf bank_mask:0xf
	v_mov_b32_dpp v142, v118 row_shr:2 row_mask:0xf bank_mask:0xf
	v_fma_f32 v78, v128, v118, v132
	v_fma_f32 v65, v124, v110, v78
	v_fma_f32 v65, v120, v142, v65
	v_mov_b32_dpp v108, v119 row_shr:1 row_mask:0xf bank_mask:0xf
	v_mov_b32_dpp v167, v116 row_ror:1 row_mask:0xf bank_mask:0xf
	v_mov_b32_dpp v109, v119 row_shr:2 row_mask:0xf bank_mask:0xf
	v_fma_f32 v79, v129, v119, v133
	v_fma_f32 v67, v125, v108, v79
	v_fma_f32 v67, v121, v109, v67
	v_cndmask_b32_e64 v78, v167, v106, s[8:9]
	v_mov_b32_dpp v169, v117 row_ror:1 row_mask:0xf bank_mask:0xf
	v_mov_b32_dpp v107, v116 row_shr:2 row_mask:0xf bank_mask:0xf
	v_fma_f32 v106, v130, v116, v134
	s_nop 0
	v_fma_f32 v78, v126, v78, v106
	v_mov_b32_dpp v172, v117 row_ror:2 row_mask:0xf bank_mask:0xf
	v_fma_f32 v78, v122, v107, v78
	v_cndmask_b32_e64 v79, v169, v104, s[8:9]
	v_cndmask_b32_e64 v104, v105, v172, s[10:11]
	v_fma_f32 v105, v131, v117, v135
	s_nop 0
	v_fma_f32 v79, v127, v79, v105
	s_nop 0
	v_fma_f32 v79, v123, v104, v79
	v_add_u32_e32 v104, 0xb0, v201
	v_cmp_gt_i32_e32 vcc, s68, v104
	s_and_b64 s[86:87], s[20:21], vcc
	v_add_u32_e32 v115, s59, v104
	s_and_saveexec_b64 s[88:89], s[86:87]
	s_cbranch_execz .LBB0_914
	v_mul_f32_e32 v104, 0xbfb8aa3b, v77
	v_exp_f32_e32 v104, v104
	s_nop 0
	v_add_f32_e32 v104, 1.0, v104
	v_rcp_f32_e32 v104, v104
	s_nop 0
	v_mul_f32_e32 v77, v77, v104
	v_mul_f32_e32 v77, v77, v79
	v_mul_f32_e32 v79, 0xbfb8aa3b, v76
	v_exp_f32_e32 v79, v79
	s_nop 0
	v_add_f32_e32 v79, 1.0, v79
	v_rcp_f32_e32 v79, v79
	s_nop 0
	v_mul_f32_e32 v76, v76, v79
	v_mul_f32_e32 v76, v76, v78
	v_mul_f32_e32 v78, 0xbfb8aa3b, v66
	v_exp_f32_e32 v78, v78
	s_nop 0
	v_add_f32_e32 v78, 1.0, v78
	v_rcp_f32_e32 v78, v78
	s_nop 0
	v_mul_f32_e32 v66, v66, v78
	v_mul_f32_e32 v66, v66, v67
	v_mul_f32_e32 v67, 0xbfb8aa3b, v64
	v_exp_f32_e32 v67, v67
	s_nop 0
	v_add_f32_e32 v67, 1.0, v67
	v_rcp_f32_e32 v67, v67
	s_nop 0
	v_mul_f32_e32 v64, v64, v67
	v_mul_f32_e32 v64, v64, v65
	v_cvt_pk_bf16_f32 v64, v64, v66
	v_mul_u32_u24_e32 v66, s69, v115
	v_lshl_add_u32 v66, v192, 1, v66
	v_cvt_pk_bf16_f32 v65, v76, v77
	global_store_dwordx2 v66, v[64:65], s[36:37]

; __device__ __forceinline__ unsigned cvt_pk_bf16(float lo, float hi) { unsigned r; asm volatile("v_cvt_pk_bf16_f32 %0, %1, %2" : "=v"(r) : "v"(lo), "v"(hi)); return r; }
; __device__ __forceinline__ float sigmoid_f(float x) { return __builtin_amdgcn_rcpf(1.0f + __builtin_amdgcn_exp2f(-1.4426950408889634f * x)); }
; __device__ __forceinline__ float dpp_ror1(float v) { return __builtin_bit_cast(float, __builtin_amdgcn_update_dpp(0, __builtin_bit_cast(int, v), 0x121, 0xf, 0xf, false)); }
; __device__ __forceinline__ float dpp_ror2(float v) { return __builtin_bit_cast(float, __builtin_amdgcn_update_dpp(0, __builtin_bit_cast(int, v), 0x122, 0xf, 0xf, false)); }
; __device__ __forceinline__ float fma_s(float a, float b, float c) { float r; asm("v_fma_f32 %0, %1, %2, %3" : "=v"(r) : "v"(a), "v"(b), "v"(c)); return r; }
;     __device__ __forceinline__ void operator()(const f32x4 (&acc)[2][2][4][2], const Unit& u, int wr, int wc, int fr, int fq) const {
;     ...
;                 for (int m = 0; m < 4; ++m) {
;                     f32x4 cur[2] = {acc[ai][0][m][n] * r2v[ai][m], acc[ai][1][m][n] * r2v[ai][m]};
;                     if (first && ai == 0 && wr == 0 && m == 0 && fr < 2) { cur[0] = zero4; cur[1] = zero4; }
;                     f32x4 r1[2], r2[2], av[2];
; #pragma unroll
;                     for (int bj = 0; bj < 2; ++bj)
; #pragma unroll
;                         for (int e = 0; e < 4; ++e) { r1[bj][e] = dpp_ror1(cur[bj][e]); r2[bj][e] = dpp_ror2(cur[bj][e]); }
; #pragma unroll
;                     for (int bj = 0; bj < 2; ++bj)
; #pragma unroll
;                         for (int e = 0; e < 4; ++e) { const float p1 = fr >= 1 ? r1[bj][e] : pr1[bj][e], p2 = fr >= 2 ? r2[bj][e] : pr2[bj][e];
;                             av[bj][e] = fma_s(w0[bj][e], p2, fma_s(w1[bj][e], p1, fma_s(w2[bj][e], cur[bj][e], bb[bj][e]))); }
;                     float o[4];
; #pragma unroll
;                     for (int e = 0; e < 4; ++e) o[e] = av[0][e] * sigmoid_f(av[0][e]) * av[1][e];
;                     const int lr = ai * HALF + wr * 64 + m * 16 + fr, t = t0 + lr;
;                     if (lr >= 2 && t < 4096) { u32x2 w; w.x = cvt_pk_bf16(o[0], o[1]); w.y = cvt_pk_bf16(o[2], o[3]);
;                         *(u32x2*)(gout + (size_t)(b * 4096 + t) * FF + j0 + n * 4) = w; }
.LBB0_922:
	s_or_b64 exec, exec, s[66:67]
	v_mov_b32_e32 v197, v196
	v_pk_mul_f32 v[36:37], v[36:37], v[196:197]
	v_pk_mul_f32 v[50:51], v[32:33], v[196:197]
	v_mov_b32_e32 v48, v196
	v_mov_b32_e32 v49, v196
	v_pk_mul_f32 v[38:39], v[38:39], v[48:49]
	v_pk_mul_f32 v[48:49], v[34:35], v[48:49]
	v_mov_b32_dpp v62, v36 row_shr:1 row_mask:0xf bank_mask:0xf
	v_mov_b32_dpp v63, v36 row_shr:2 row_mask:0xf bank_mask:0xf
	v_fma_f32 v36, v96, v36, v100
	v_fma_f32 v32, v92, v62, v36
	v_fma_f32 v32, v88, v63, v32
	v_mov_b32_dpp v60, v37 row_shr:1 row_mask:0xf bank_mask:0xf
	v_mov_b32_dpp v52, v38 row_ror:1 row_mask:0xf bank_mask:0xf
	v_mov_b32_dpp v61, v37 row_shr:2 row_mask:0xf bank_mask:0xf
	v_fma_f32 v35, v97, v37, v101
	v_mov_b32_dpp v53, v38 row_ror:2 row_mask:0xf bank_mask:0xf
	v_fma_f32 v33, v93, v60, v35
	v_fma_f32 v33, v89, v61, v33
	v_cndmask_b32_e64 v34, v52, v58, s[8:9]
	v_mov_b32_dpp v54, v39 row_ror:1 row_mask:0xf bank_mask:0xf
	v_cndmask_b32_e64 v35, v59, v53, s[10:11]
	v_fma_f32 v36, v98, v38, v102
	v_mov_b32_dpp v55, v39 row_ror:2 row_mask:0xf bank_mask:0xf
	v_fma_f32 v34, v94, v34, v36
	v_fma_f32 v34, v90, v35, v34
	v_cndmask_b32_e64 v35, v54, v47, s[8:9]
	v_cndmask_b32_e64 v36, v57, v55, s[10:11]
	v_fma_f32 v37, v99, v39, v103
	v_fma_f32 v35, v95, v35, v37
	v_fma_f32 v36, v91, v36, v35
	v_mov_b32_dpp v46, v50 row_shr:1 row_mask:0xf bank_mask:0xf
	v_mov_b32_dpp v56, v50 row_shr:2 row_mask:0xf bank_mask:0xf
	v_fma_f32 v38, v80, v50, v84
	v_mov_b32_dpp v67, v51 row_ror:2 row_mask:0xf bank_mask:0xf
	v_fma_f32 v35, v72, v46, v38
	v_fma_f32 v35, v68, v56, v35
	v_mov_b32_dpp v44, v51 row_shr:1 row_mask:0xf bank_mask:0xf
	v_mov_b32_dpp v76, v48 row_ror:1 row_mask:0xf bank_mask:0xf
	v_cndmask_b32_e64 v38, v45, v67, s[10:11]
	v_fma_f32 v39, v81, v51, v85
	v_mov_b32_dpp v77, v48 row_ror:2 row_mask:0xf bank_mask:0xf
	v_fma_f32 v37, v73, v44, v39
	v_fma_f32 v37, v69, v38, v37
	v_cndmask_b32_e64 v38, v76, v42, s[8:9]
	v_mov_b32_dpp v78, v49 row_ror:1 row_mask:0xf bank_mask:0xf
	v_cndmask_b32_e64 v39, v43, v77, s[10:11]
	v_fma_f32 v42, v82, v48, v86
	v_mov_b32_dpp v79, v49 row_ror:2 row_mask:0xf bank_mask:0xf
	v_fma_f32 v38, v74, v38, v42
	s_nop 0
	v_fma_f32 v38, v70, v39, v38
	v_cndmask_b32_e64 v39, v78, v40, s[8:9]
	v_cndmask_b32_e64 v40, v41, v79, s[10:11]
	v_fma_f32 v41, v83, v49, v87
	s_nop 0
	v_fma_f32 v39, v75, v39, v41
	s_nop 0
	v_fma_f32 v39, v71, v40, v39
	s_and_saveexec_b64 s[0:1], s[64:65]
	s_cbranch_execz .LBB0_924
	v_mul_f32_e32 v40, 0xbfb8aa3b, v36
	v_exp_f32_e32 v40, v40
	v_mul_f32_e32 v41, 0xbfb8aa3b, v34
	v_mul_f32_e32 v42, 0xbfb8aa3b, v33
	v_exp_f32_e32 v41, v41
	v_add_f32_e32 v40, 1.0, v40
	v_rcp_f32_e32 v40, v40
	v_exp_f32_e32 v42, v42
	v_add_f32_e32 v41, 1.0, v41
	v_rcp_f32_e32 v41, v41
	v_mul_f32_e32 v36, v36, v40
	v_mul_f32_e32 v36, v36, v39
	v_mul_f32_e32 v39, 0xbfb8aa3b, v32
	v_exp_f32_e32 v39, v39
	v_add_f32_e32 v40, 1.0, v42
	v_rcp_f32_e32 v40, v40
	v_mul_f32_e32 v34, v34, v41
	v_add_f32_e32 v39, 1.0, v39
	v_rcp_f32_e32 v39, v39
	v_mul_f32_e32 v33, v33, v40
	v_mul_f32_e32 v34, v34, v38
	v_mul_f32_e32 v33, v33, v37
	v_mul_f32_e32 v32, v32, v39
	v_mul_f32_e32 v32, v32, v35
	v_cvt_pk_bf16_f32 v32, v32, v33
	v_cvt_pk_bf16_f32 v33, v34, v36
	v_mul_u32_u24_e32 v34, s69, v227
	v_lshl_add_u32 v34, v192, 1, v34
	global_store_dwordx2 v34, v[32:33], s[36:37] offset:8

; __device__ __forceinline__ unsigned cvt_pk_bf16(float lo, float hi) { unsigned r; asm volatile("v_cvt_pk_bf16_f32 %0, %1, %2" : "=v"(r) : "v"(lo), "v"(hi)); return r; }
; __device__ __forceinline__ float sigmoid_f(float x) { return __builtin_amdgcn_rcpf(1.0f + __builtin_amdgcn_exp2f(-1.4426950408889634f * x)); }
; __device__ __forceinline__ float dpp_ror1(float v) { return __builtin_bit_cast(float, __builtin_amdgcn_update_dpp(0, __builtin_bit_cast(int, v), 0x121, 0xf, 0xf, false)); }
; __device__ __forceinline__ float dpp_ror2(float v) { return __builtin_bit_cast(float, __builtin_amdgcn_update_dpp(0, __builtin_bit_cast(int, v), 0x122, 0xf, 0xf, false)); }
; __device__ __forceinline__ float fma_s(float a, float b, float c) { float r; asm("v_fma_f32 %0, %1, %2, %3" : "=v"(r) : "v"(a), "v"(b), "v"(c)); return r; }
;     __device__ __forceinline__ void operator()(const f32x4 (&acc)[2][2][4][2], const Unit& u, int wr, int wc, int fr, int fq) const {
;     ...
;                 for (int m = 0; m < 4; ++m) {
;                     f32x4 cur[2] = {acc[ai][0][m][n] * r2v[ai][m], acc[ai][1][m][n] * r2v[ai][m]};
;                     if (first && ai == 0 && wr == 0 && m == 0 && fr < 2) { cur[0] = zero4; cur[1] = zero4; }
;                     f32x4 r1[2], r2[2], av[2];
; #pragma unroll
;                     for (int bj = 0; bj < 2; ++bj)
; #pragma unroll
;                         for (int e = 0; e < 4; ++e) { r1[bj][e] = dpp_ror1(cur[bj][e]); r2[bj][e] = dpp_ror2(cur[bj][e]); }
; #pragma unroll
;                     for (int bj = 0; bj < 2; ++bj)
; #pragma unroll
;                         for (int e = 0; e < 4; ++e) { const float p1 = fr >= 1 ? r1[bj][e] : pr1[bj][e], p2 = fr >= 2 ? r2[bj][e] : pr2[bj][e];
;                             av[bj][e] = fma_s(w0[bj][e], p2, fma_s(w1[bj][e], p1, fma_s(w2[bj][e], cur[bj][e], bb[bj][e]))); }
;                     float o[4];
; #pragma unroll
;                     for (int e = 0; e < 4; ++e) o[e] = av[0][e] * sigmoid_f(av[0][e]) * av[1][e];
;                     const int lr = ai * HALF + wr * 64 + m * 16 + fr, t = t0 + lr;
;                     if (lr >= 2 && t < 4096) { u32x2 w; w.x = cvt_pk_bf16(o[0], o[1]); w.y = cvt_pk_bf16(o[2], o[3]);
;                         *(u32x2*)(gout + (size_t)(b * 4096 + t) * FF + j0 + n * 4) = w; }
.LBB0_932:
	s_or_b64 exec, exec, s[0:1]
	v_mov_b32_e32 v195, v194
	v_pk_mul_f32 v[4:5], v[4:5], v[194:195]
	v_pk_mul_f32 v[18:19], v[0:1], v[194:195]
	v_mov_b32_e32 v16, v194
	v_mov_b32_e32 v17, v194
	v_pk_mul_f32 v[6:7], v[6:7], v[16:17]
	v_pk_mul_f32 v[16:17], v[2:3], v[16:17]
	v_mov_b32_dpp v30, v4 row_shr:1 row_mask:0xf bank_mask:0xf
	v_mov_b32_dpp v31, v4 row_shr:2 row_mask:0xf bank_mask:0xf
	v_fma_f32 v4, v96, v4, v100
	v_fma_f32 v0, v92, v30, v4
	v_fma_f32 v0, v88, v31, v0
	v_mov_b32_dpp v28, v5 row_shr:1 row_mask:0xf bank_mask:0xf
	v_mov_b32_dpp v29, v5 row_shr:2 row_mask:0xf bank_mask:0xf
	v_fma_f32 v3, v97, v5, v101
	v_fma_f32 v1, v93, v28, v3
	v_fma_f32 v1, v89, v29, v1
	v_mov_b32_dpp v26, v6 row_shr:1 row_mask:0xf bank_mask:0xf
	v_mov_b32_dpp v27, v6 row_shr:2 row_mask:0xf bank_mask:0xf
	v_fma_f32 v4, v98, v6, v102
	v_fma_f32 v2, v94, v26, v4
	v_fma_f32 v2, v90, v27, v2
	v_mov_b32_dpp v15, v7 row_shr:1 row_mask:0xf bank_mask:0xf
	v_mov_b32_dpp v25, v7 row_shr:2 row_mask:0xf bank_mask:0xf
	v_fma_f32 v5, v99, v7, v103
	v_fma_f32 v3, v95, v15, v5
	v_fma_f32 v4, v91, v25, v3
	v_mov_b32_dpp v14, v18 row_shr:1 row_mask:0xf bank_mask:0xf
	v_mov_b32_dpp v24, v18 row_shr:2 row_mask:0xf bank_mask:0xf
	v_fma_f32 v6, v80, v18, v84
	v_fma_f32 v3, v72, v14, v6
	v_fma_f32 v3, v68, v24, v3
	v_mov_b32_dpp v12, v19 row_shr:1 row_mask:0xf bank_mask:0xf
	v_mov_b32_dpp v36, v16 row_ror:1 row_mask:0xf bank_mask:0xf
	v_mov_b32_dpp v13, v19 row_shr:2 row_mask:0xf bank_mask:0xf
	v_fma_f32 v7, v81, v19, v85
	v_fma_f32 v5, v73, v12, v7
	v_fma_f32 v5, v69, v13, v5
	v_cndmask_b32_e64 v6, v36, v10, s[8:9]
	v_mov_b32_dpp v38, v17 row_ror:1 row_mask:0xf bank_mask:0xf
	v_mov_b32_dpp v11, v16 row_shr:2 row_mask:0xf bank_mask:0xf
	v_fma_f32 v10, v82, v16, v86
	v_mov_b32_dpp v39, v17 row_ror:2 row_mask:0xf bank_mask:0xf
	v_fma_f32 v6, v74, v6, v10
	s_nop 0
	v_fma_f32 v6, v70, v11, v6
	v_cndmask_b32_e64 v7, v38, v8, s[8:9]
	v_cndmask_b32_e64 v8, v9, v39, s[10:11]
	v_fma_f32 v9, v83, v17, v87
	s_nop 0
	v_fma_f32 v7, v75, v7, v9
	s_nop 0
	v_fma_f32 v7, v71, v8, v7
	s_and_saveexec_b64 s[0:1], s[86:87]
	s_cbranch_execz .LBB0_934
	v_mul_f32_e32 v8, 0xbfb8aa3b, v4
	v_exp_f32_e32 v8, v8
	v_mul_f32_e32 v9, 0xbfb8aa3b, v2
	v_mul_f32_e32 v10, 0xbfb8aa3b, v1
	v_exp_f32_e32 v9, v9
	v_add_f32_e32 v8, 1.0, v8
	v_rcp_f32_e32 v8, v8
	v_exp_f32_e32 v10, v10
	v_add_f32_e32 v9, 1.0, v9
	v_rcp_f32_e32 v9, v9
	v_mul_f32_e32 v4, v4, v8
	v_mul_f32_e32 v4, v4, v7
	v_mul_f32_e32 v7, 0xbfb8aa3b, v0
	v_exp_f32_e32 v7, v7
	v_add_f32_e32 v8, 1.0, v10
	v_rcp_f32_e32 v8, v8
	v_mul_f32_e32 v2, v2, v9
	v_add_f32_e32 v7, 1.0, v7
	v_rcp_f32_e32 v7, v7
	v_mul_f32_e32 v1, v1, v8
	v_mul_f32_e32 v2, v2, v6
	v_mul_f32_e32 v1, v1, v5
	v_mul_f32_e32 v0, v0, v7
	v_mul_f32_e32 v0, v0, v3
	v_cvt_pk_bf16_f32 v0, v0, v1
	v_cvt_pk_bf16_f32 v1, v2, v4
	v_mul_u32_u24_e32 v2, s69, v115
	v_lshl_add_u32 v2, v192, 1, v2
	global_store_dwordx2 v2, v[0:1], s[36:37] offset:8
